# cache policy on the final RMSNorm: nt on the once-read residual rows, write-through (sc1) on the 64 MB f32 output stores
# speedup vs baseline: 1.0189x; 1.0189x over previous
.LBB0_878:
	s_add_i32 s6, s56, s52
	s_cmpk_lt_i32 s6, 0x4000
	s_cselect_b64 s[2:3], -1, 0
	s_and_b64 s[0:1], s[2:3], exec
	s_cselect_b32 s0, s6, s56
	s_ashr_i32 s57, s56, 31
	s_lshl_b64 s[8:9], s[56:57], 3
	s_add_u32 s8, s4, s8
	s_addc_u32 s9, s5, s9
	global_load_dwordx2 v[20:21], v42, s[8:9]
	s_ashr_i32 s1, s0, 31
	s_lshl_b64 s[8:9], s[0:1], 3
	s_waitcnt vmcnt(0)
	v_readfirstlane_b32 s7, v21
	v_readfirstlane_b32 s10, v20
	s_xor_b32 s10, s10, s7
	s_flbit_i32 s7, s7
	s_ashr_i32 s10, s10, 31
	s_add_i32 s7, s7, -1
	s_add_i32 s10, s10, 32
	s_min_u32 s7, s7, s10
	s_sub_i32 s10, 32, s7
	s_add_u32 s8, s4, s8
	s_addc_u32 s9, s5, s9
	global_load_dwordx2 v[30:31], v42, s[8:9]
	s_lshl_b64 s[8:9], s[56:57], 11
	v_lshl_add_u64 v[24:25], v[16:17], 0, s[8:9]
	global_load_dwordx2 v[44:45], v[24:25], off nt
	s_lshl_b64 s[8:9], s[0:1], 11
	v_lshl_add_u64 v[28:29], v[16:17], 0, s[8:9]
	global_load_dwordx2 v[38:39], v[24:25], off offset:512 nt
	global_load_dwordx2 v[34:35], v[24:25], off offset:1024 nt
	global_load_dwordx2 v[40:41], v[28:29], off nt
	global_load_dwordx2 v[36:37], v[28:29], off offset:512 nt
	global_load_dwordx2 v[32:33], v[28:29], off offset:1024 nt
	global_load_dwordx2 v[26:27], v[24:25], off offset:1536 nt
	global_load_dwordx2 v[22:23], v[28:29], off offset:1536 nt
	v_lshlrev_b64 v[20:21], s7, v[20:21]
	v_min_u32_e32 v20, 1, v20
	v_or_b32_e32 v20, v21, v20
	s_lshl_b64 s[0:1], s[0:1], 12
	v_cvt_f32_i32_e32 v28, v20
	v_lshl_add_u64 v[20:21], v[18:19], 0, s[0:1]
	s_lshl_b64 s[8:9], s[56:57], 12
	v_lshl_add_u64 v[24:25], v[18:19], 0, s[8:9]
	v_ldexp_f32 v28, v28, s10
	v_mul_f32_e32 v28, 0x35800000, v28
	v_fmamk_f32 v28, v28, 0x3a800000, v43
	v_rsq_f32_e32 v28, v28
	s_waitcnt vmcnt(8)
	v_readfirstlane_b32 s0, v31
	v_readfirstlane_b32 s1, v30
	s_xor_b32 s1, s1, s0
	s_flbit_i32 s0, s0
	s_ashr_i32 s1, s1, 31
	s_add_i32 s0, s0, -1
	s_add_i32 s1, s1, 32
	s_min_u32 s0, s0, s1
	v_lshlrev_b64 v[30:31], s0, v[30:31]
	v_min_u32_e32 v29, 1, v30
	v_or_b32_e32 v29, v31, v29
	v_cvt_f32_i32_e32 v29, v29
	s_waitcnt vmcnt(7)
	v_lshlrev_b32_e32 v46, 16, v44
	v_and_b32_e32 v47, 0xffff0000, v44
	v_lshlrev_b32_e32 v44, 16, v45
	v_and_b32_e32 v45, 0xffff0000, v45
	s_sub_i32 s0, 32, s0
	v_pk_mul_f32 v[48:49], v[28:29], v[46:47] op_sel_hi:[0,1]
	v_pk_mul_f32 v[44:45], v[28:29], v[44:45] op_sel_hi:[0,1]
	v_ldexp_f32 v29, v29, s0
	v_mul_f32_e32 v29, 0x35800000, v29
	v_fmamk_f32 v29, v29, 0x3a800000, v43
	v_rsq_f32_e32 v30, v29
	v_pk_mul_f32 v[46:47], v[2:3], v[44:45]
	v_pk_mul_f32 v[44:45], v[0:1], v[48:49]
	s_cmpk_gt_i32 s6, 0x3fff
	v_mov_b32_e32 v31, v30
	global_store_dwordx4 v[24:25], v[44:47], off sc1
	s_cbranch_scc1 .LBB0_880
	s_waitcnt vmcnt(5)
	v_lshlrev_b32_e32 v44, 16, v40
	v_and_b32_e32 v45, 0xffff0000, v40
	v_lshlrev_b32_e32 v40, 16, v41
	v_and_b32_e32 v41, 0xffff0000, v41
	v_mov_b32_e32 v46, v30
	v_mov_b32_e32 v47, v30
	v_pk_mul_f32 v[44:45], v[30:31], v[44:45]
	v_pk_mul_f32 v[40:41], v[46:47], v[40:41]
	v_pk_mul_f32 v[44:45], v[0:1], v[44:45]
	v_pk_mul_f32 v[46:47], v[2:3], v[40:41]
	global_store_dwordx4 v[20:21], v[44:47], off sc1
.LBB0_880:
	v_mov_b32_e32 v29, v28
	s_waitcnt vmcnt(5)
	v_lshlrev_b32_e32 v40, 16, v38
	v_and_b32_e32 v41, 0xffff0000, v38
	v_lshlrev_b32_e32 v44, 16, v39
	v_and_b32_e32 v45, 0xffff0000, v39
	v_mov_b32_e32 v38, v28
	v_mov_b32_e32 v39, v28
	v_pk_mul_f32 v[40:41], v[28:29], v[40:41]
	v_pk_mul_f32 v[44:45], v[38:39], v[44:45]
	s_andn2_b64 vcc, exec, s[2:3]
	v_pk_mul_f32 v[46:47], v[6:7], v[44:45]
	v_pk_mul_f32 v[44:45], v[4:5], v[40:41]
	v_cndmask_b32_e64 v40, 0, 1, s[2:3]
	v_cmp_ne_u32_e64 s[0:1], 1, v40
	global_store_dwordx4 v[24:25], v[44:47], off offset:1024 sc1
	s_cbranch_vccnz .LBB0_882
	s_waitcnt vmcnt(5)
	v_lshlrev_b32_e32 v40, 16, v36
	v_and_b32_e32 v41, 0xffff0000, v36
	v_lshlrev_b32_e32 v36, 16, v37
	v_and_b32_e32 v37, 0xffff0000, v37
	v_mov_b32_e32 v44, v30
	v_mov_b32_e32 v45, v30
	v_pk_mul_f32 v[40:41], v[30:31], v[40:41]
	v_pk_mul_f32 v[36:37], v[44:45], v[36:37]
	v_pk_mul_f32 v[44:45], v[4:5], v[40:41]
	v_pk_mul_f32 v[46:47], v[6:7], v[36:37]
	global_store_dwordx4 v[20:21], v[44:47], off offset:1024 sc1
.LBB0_882:
	s_waitcnt vmcnt(5)
	v_lshlrev_b32_e32 v36, 16, v34
	v_and_b32_e32 v37, 0xffff0000, v34
	v_lshlrev_b32_e32 v34, 16, v35
	v_and_b32_e32 v35, 0xffff0000, v35
	v_pk_mul_f32 v[40:41], v[28:29], v[36:37]
	v_pk_mul_f32 v[34:35], v[38:39], v[34:35]
	s_and_b64 vcc, exec, s[0:1]
	v_pk_mul_f32 v[36:37], v[10:11], v[34:35]
	v_pk_mul_f32 v[34:35], v[8:9], v[40:41]
	global_store_dwordx4 v[24:25], v[34:37], off offset:2048 sc1
	s_cbranch_vccnz .LBB0_884
	s_waitcnt vmcnt(5)
	v_lshlrev_b32_e32 v34, 16, v32
	v_and_b32_e32 v35, 0xffff0000, v32
	v_lshlrev_b32_e32 v32, 16, v33
	v_and_b32_e32 v33, 0xffff0000, v33
	v_pk_mul_f32 v[36:37], v[30:31], v[34:35]
	v_mov_b32_e32 v34, v30
	v_mov_b32_e32 v35, v30
	v_pk_mul_f32 v[32:33], v[34:35], v[32:33]
	s_nop 0
	v_pk_mul_f32 v[34:35], v[10:11], v[32:33]
	v_pk_mul_f32 v[32:33], v[8:9], v[36:37]
	global_store_dwordx4 v[20:21], v[32:35], off offset:2048 sc1
.LBB0_884:
	s_waitcnt vmcnt(4)
	s_nop 0
	v_lshlrev_b32_e32 v32, 16, v26
	v_and_b32_e32 v33, 0xffff0000, v26
	v_lshlrev_b32_e32 v26, 16, v27
	v_and_b32_e32 v27, 0xffff0000, v27
	v_pk_mul_f32 v[32:33], v[28:29], v[32:33]
	v_mov_b32_e32 v29, v28
	v_pk_mul_f32 v[26:27], v[28:29], v[26:27]
	s_and_b64 vcc, exec, s[0:1]
	v_pk_mul_f32 v[28:29], v[14:15], v[26:27]
	v_pk_mul_f32 v[26:27], v[12:13], v[32:33]
	global_store_dwordx4 v[24:25], v[26:29], off offset:3072 sc1
	s_cbranch_vccnz .LBB0_877
	s_waitcnt vmcnt(4)
	v_lshlrev_b32_e32 v24, 16, v22
	v_and_b32_e32 v25, 0xffff0000, v22
	v_lshlrev_b32_e32 v22, 16, v23
	v_and_b32_e32 v23, 0xffff0000, v23
	v_pk_mul_f32 v[26:27], v[30:31], v[24:25]
	v_mov_b32_e32 v31, v30
	v_pk_mul_f32 v[22:23], v[30:31], v[22:23]
	s_nop 0
	v_pk_mul_f32 v[24:25], v[14:15], v[22:23]
	v_pk_mul_f32 v[22:23], v[12:13], v[26:27]
	global_store_dwordx4 v[20:21], v[22:25], off offset:3072 sc1
	s_branch .LBB0_877
